# NSA sel/window tile loops: next-tile K LDS writes moved from tile end to right after the QK MFMAs and V writes into the PV section (spreads the LDS store burst, removes the exposed store latency befor
# speedup vs baseline: 1.0010x; 1.0010x over previous
; #define SBAR() __builtin_amdgcn_sched_barrier(0)
; DI int crow(int r, int hi) { return (r & 3) + 8 * (r >> 2) + 4 * hi; }
; #pragma unroll
;     for (int r = 0; r < 16; ++r) { p0[r] = 0.f; p1[r] = 0.f; }
;     int rowb = r32 * (2 * D), swz = (r32 & 7) << 4; asm volatile("" : "+v"(rowb), "+v"(swz));
; #pragma unroll
;     for (int g4 = 0; g4 < D / (16 * NBT); ++g4) {
;         bf16x8 kf[2 * NBT];
; #pragma unroll
;         for (int i = 0; i < NBT; ++i) { const int cb = ((g4 * NBT + i) * 16 + hi * 8) * 2;
;             const char* kp = Ks + rowb + (cb ^ swz);
;             kf[2 * i] = *reinterpret_cast<const bf16x8*>(kp);
;             kf[2 * i + 1] = *reinterpret_cast<const bf16x8*>(kp + 64 * D); }
;         SBAR();
; #pragma unroll
;         for (int i = 0; i < NBT; ++i) {
;             p0 = __builtin_amdgcn_mfma_f32_32x32x16_bf16(kf[2 * i], qr[g4 * NBT + i], p0, 0, 0, 0);
;             p1 = __builtin_amdgcn_mfma_f32_32x32x16_bf16(kf[2 * i + 1], qr[g4 * NBT + i], p1, 0, 0, 0); }
;         SBAR();
;     }
; }
; template <int D, class MaskF>
; DI void tile_finish(Core<D>& c, f32x16& p0, f32x16& p1, int j, const MaskF& mk, float* ws, int vb, int r32, int hi) {
;     if (mk.partial(j)) { const int kb = 64 * j;
; #pragma unroll
;         for (int r = 0; r < 16; ++r) { const int k0 = kb + crow(r, hi); if (!mk.ok(j, k0)) p0[r] = NEGS; if (!mk.ok(j, k0 + 32)) p1[r] = NEGS; } }
.LBB0_862:
	s_lshl_b32 s61, s10, 14
	v_mov_b32_e32 v0, v171
	v_mov_b32_e32 v177, v204
	s_add_i32 s14, s61, 0
	v_add_u32_e32 v74, 32, v205
	v_add_u32_e32 v0, s14, v0
	v_xad_u32 v70, v177, v205, v0
	v_xad_u32 v74, v177, v74, v0
	ds_read_b128 v[66:69], v70
	ds_read_b128 v[70:73], v70 offset:8192
	ds_read_b128 v[194:197], v74
	ds_read_b128 v[220:223], v74 offset:8192
	v_add_u32_e32 v74, 64, v205
	v_xad_u32 v74, v177, v74, v0
	ds_read_b128 v[224:227], v74
	ds_read_b128 v[228:231], v74 offset:8192
	v_add_u32_e32 v74, 0x60, v205
	v_xad_u32 v74, v177, v74, v0
	ds_read_b128 v[232:235], v74
	ds_read_b128 v[236:239], v74 offset:8192
	s_waitcnt lgkmcnt(7)
	v_mfma_f32_32x32x16_bf16 v[82:97], v[66:69], v[112:115], 0
	s_waitcnt lgkmcnt(6)
	v_mfma_f32_32x32x16_bf16 v[66:81], v[70:73], v[112:115], 0
	s_waitcnt lgkmcnt(5)
	v_mfma_f32_32x32x16_bf16 v[82:97], v[194:197], v[116:119], v[82:97]
	v_xad_u32 v186, v177, v209, v0
	ds_read_b128 v[194:197], v186
	s_waitcnt lgkmcnt(5)
	v_mfma_f32_32x32x16_bf16 v[66:81], v[220:223], v[116:119], v[66:81]
	ds_read_b128 v[220:223], v186 offset:8192
	v_xad_u32 v186, v177, v210, v0
	s_waitcnt lgkmcnt(5)
	v_mfma_f32_32x32x16_bf16 v[82:97], v[224:227], v[120:123], v[82:97]
	ds_read_b128 v[224:227], v186
	s_waitcnt lgkmcnt(5)
	v_mfma_f32_32x32x16_bf16 v[66:81], v[228:231], v[120:123], v[66:81]
	ds_read_b128 v[228:231], v186 offset:8192
	v_xad_u32 v186, v177, v211, v0
	v_xad_u32 v0, v177, v212, v0
	s_waitcnt lgkmcnt(5)
	v_mfma_f32_32x32x16_bf16 v[82:97], v[232:235], v[124:127], v[82:97]
	ds_read_b128 v[232:235], v186
	s_waitcnt lgkmcnt(5)
	v_mfma_f32_32x32x16_bf16 v[66:81], v[236:239], v[124:127], v[66:81]
	ds_read_b128 v[236:239], v186 offset:8192
	ds_read_b128 v[248:251], v0
	ds_read_b128 v[186:189], v0 offset:8192
	s_waitcnt lgkmcnt(7)
	v_mfma_f32_32x32x16_bf16 v[82:97], v[194:197], v[128:131], v[82:97]
	s_waitcnt lgkmcnt(6)
	v_mfma_f32_32x32x16_bf16 v[66:81], v[220:223], v[128:131], v[66:81]
	s_waitcnt lgkmcnt(5)
	v_mfma_f32_32x32x16_bf16 v[82:97], v[224:227], v[132:135], v[82:97]
	s_waitcnt lgkmcnt(4)
	v_mfma_f32_32x32x16_bf16 v[66:81], v[228:231], v[132:135], v[66:81]
	s_waitcnt lgkmcnt(3)
	v_mfma_f32_32x32x16_bf16 v[82:97], v[232:235], v[136:139], v[82:97]
	s_waitcnt lgkmcnt(2)
	v_mfma_f32_32x32x16_bf16 v[66:81], v[236:239], v[136:139], v[66:81]
	s_waitcnt lgkmcnt(1)
	v_mfma_f32_32x32x16_bf16 v[82:97], v[248:251], v[140:143], v[82:97]
	s_waitcnt lgkmcnt(0)
	v_mfma_f32_32x32x16_bf16 v[66:81], v[186:189], v[140:143], v[66:81]
	s_cmp_eq_u64 s[52:53], 0
	s_cbranch_scc1 .Lew_sel_kskip
	s_xor_b32 s99, s61, 0x4000
	v_add_u32_e32 v194, s99, v208
	s_waitcnt vmcnt(3)
	ds_write_b128 v194, v[98:101]
	s_waitcnt vmcnt(2)
	ds_write_b128 v194, v[102:105] offset:8192
.Lew_sel_kskip:
	s_cmp_lt_i32 s59, s91
	s_cbranch_scc1 .LBB0_866
	v_lshl_add_u32 v0, s59, 6, v206
	v_add_u32_e32 v177, 32, v0
	v_cmp_le_i32_e64 s[14:15], v177, v169
	v_add_u32_e32 v177, 33, v0
	v_cmp_le_i32_e64 s[16:17], v177, v169
	v_or_b32_e32 v177, 2, v0
	v_cmp_le_i32_e32 vcc, v0, v169
	s_nop 2
	v_cndmask_b32_e64 v67, v247, v67, s[16:17]
	v_cmp_le_i32_e64 s[16:17], v177, v169
	v_add_u32_e32 v177, 34, v0
	v_cmp_le_i32_e64 s[18:19], v177, v169
	v_or_b32_e32 v177, 3, v0
	v_cndmask_b32_e64 v66, v247, v66, s[14:15]
	v_cndmask_b32_e64 v68, v247, v68, s[18:19]
	v_cmp_le_i32_e64 s[18:19], v177, v169
	v_add_u32_e32 v177, 35, v0
	v_cmp_le_i32_e64 s[20:21], v177, v169
	v_add_u32_e32 v177, 8, v0
	v_cmp_lt_i32_e64 s[14:15], v0, v169
	v_cndmask_b32_e64 v69, v247, v69, s[20:21]
	v_cmp_le_i32_e64 s[20:21], v177, v169
	v_add_u32_e32 v177, 40, v0
	v_cmp_le_i32_e64 s[22:23], v177, v169
	v_add_u32_e32 v177, 9, v0
	s_nop 0
	v_cndmask_b32_e64 v70, v247, v70, s[22:23]
	v_cmp_le_i32_e64 s[22:23], v177, v169
	v_add_u32_e32 v177, 41, v0
	v_cmp_le_i32_e64 s[24:25], v177, v169
	v_add_u32_e32 v177, 10, v0
	s_nop 0
	v_cndmask_b32_e64 v71, v247, v71, s[24:25]
	v_cmp_le_i32_e64 s[24:25], v177, v169
	v_add_u32_e32 v177, 42, v0
	v_cmp_le_i32_e64 s[26:27], v177, v169
	v_add_u32_e32 v177, 11, v0
	s_nop 0
	v_cndmask_b32_e64 v72, v247, v72, s[26:27]
	v_cmp_le_i32_e64 s[26:27], v177, v169
	v_add_u32_e32 v177, 43, v0
	v_cmp_le_i32_e64 s[28:29], v177, v169
	v_add_u32_e32 v177, 16, v0
	s_nop 0
	v_cndmask_b32_e64 v73, v247, v73, s[28:29]
	v_cmp_le_i32_e64 s[28:29], v177, v169
	v_add_u32_e32 v177, 48, v0
	v_cmp_le_i32_e64 s[30:31], v177, v169
	v_add_u32_e32 v177, 17, v0
	s_nop 0
	v_cndmask_b32_e64 v74, v247, v74, s[30:31]
	v_cmp_le_i32_e64 s[30:31], v177, v169
	v_add_u32_e32 v177, 49, v0
	v_cmp_le_i32_e64 s[34:35], v177, v169
	v_add_u32_e32 v177, 18, v0
	s_nop 0
	v_cndmask_b32_e64 v75, v247, v75, s[34:35]
	v_cmp_le_i32_e64 s[34:35], v177, v169
	v_add_u32_e32 v177, 50, v0
	v_cmp_le_i32_e64 s[36:37], v177, v169
	v_add_u32_e32 v177, 19, v0
	s_nop 0
	v_cndmask_b32_e64 v76, v247, v76, s[36:37]
	v_cmp_le_i32_e64 s[36:37], v177, v169
	v_add_u32_e32 v177, 51, v0
	v_cmp_le_i32_e64 s[38:39], v177, v169
	v_add_u32_e32 v177, 24, v0
	s_nop 0
	v_cndmask_b32_e64 v77, v247, v77, s[38:39]
	v_cmp_le_i32_e64 s[38:39], v177, v169
	v_add_u32_e32 v177, 56, v0
	v_cmp_le_i32_e64 s[40:41], v177, v169
	v_add_u32_e32 v177, 25, v0
	s_nop 0
	v_cndmask_b32_e64 v78, v247, v78, s[40:41]
	v_cmp_le_i32_e64 s[40:41], v177, v169
	v_add_u32_e32 v177, 57, v0
	v_cmp_le_i32_e64 s[42:43], v177, v169
	v_add_u32_e32 v177, 26, v0
	s_nop 0
	v_cndmask_b32_e64 v79, v247, v79, s[42:43]
	v_cmp_le_i32_e64 s[42:43], v177, v169
	v_add_u32_e32 v177, 58, v0
	v_cmp_le_i32_e64 s[44:45], v177, v169
	v_add_u32_e32 v177, 27, v0
	v_add_u32_e32 v0, 59, v0
	v_cndmask_b32_e64 v80, v247, v80, s[44:45]
	v_cmp_le_i32_e64 s[44:45], v177, v169
	v_cmp_gt_i32_e64 s[46:47], v0, v169
	s_and_saveexec_b64 s[54:55], s[46:47]
	v_mov_b32_e32 v81, s95
	s_or_b64 exec, exec, s[54:55]
	v_cndmask_b32_e64 v83, v247, v83, s[14:15]
	v_cndmask_b32_e32 v82, v247, v82, vcc
	v_cndmask_b32_e64 v84, v247, v84, s[16:17]
	v_cndmask_b32_e64 v85, v247, v85, s[18:19]
	v_cndmask_b32_e64 v86, v247, v86, s[20:21]
	v_cndmask_b32_e64 v87, v247, v87, s[22:23]
	v_cndmask_b32_e64 v88, v247, v88, s[24:25]
	v_cndmask_b32_e64 v89, v247, v89, s[26:27]
	v_cndmask_b32_e64 v90, v247, v90, s[28:29]
	v_cndmask_b32_e64 v91, v247, v91, s[30:31]
	v_cndmask_b32_e64 v92, v247, v92, s[34:35]
	v_cndmask_b32_e64 v93, v247, v93, s[36:37]
	v_cndmask_b32_e64 v94, v247, v94, s[38:39]
	v_cndmask_b32_e64 v95, v247, v95, s[40:41]
	v_cndmask_b32_e64 v96, v247, v96, s[42:43]
	v_cndmask_b32_e64 v97, v247, v97, s[44:45]

; #define SBAR() __builtin_amdgcn_sched_barrier(0)
; template <int OFF> DI s16x4 tr_read(int vb) { s16x4 r; asm volatile("ds_read_b64_tr_b16 %0, %1 offset:%2" : "=&v"(r) : "v"(vb), "i"(OFF) : "memory"); return r; }
; #define LBAR() asm volatile("s_waitcnt lgkmcnt(0)\n\ts_barrier" ::: "memory")
; template <int D, int D0> DI void pv_one(f32x16& od, int vb, bf16x8 pa0, bf16x8 pa1, bf16x8 pa2, bf16x8 pa3) {
;     const s16x4 l0 = tr_read<v_rd_off<D>(D0, 0, 0)>(vb), h0 = tr_read<v_rd_off<D>(D0, 0, 1)>(vb), l1 = tr_read<v_rd_off<D>(D0, 1, 0)>(vb), h1 = tr_read<v_rd_off<D>(D0, 1, 1)>(vb);
;     const s16x4 l2 = tr_read<v_rd_off<D>(D0, 2, 0)>(vb), h2 = tr_read<v_rd_off<D>(D0, 2, 1)>(vb), l3 = tr_read<v_rd_off<D>(D0, 3, 0)>(vb), h3 = tr_read<v_rd_off<D>(D0, 3, 1)>(vb);
;     asm volatile("s_waitcnt lgkmcnt(0)" ::: "memory"); SBAR();
;     ...
;     od = __builtin_amdgcn_mfma_f32_32x32x16_bf16(pa0, PK(l0, h0), od, 0, 0, 0);
;     od = __builtin_amdgcn_mfma_f32_32x32x16_bf16(pa1, PK(l1, h1), od, 0, 0, 0);
;     od = __builtin_amdgcn_mfma_f32_32x32x16_bf16(pa2, PK(l2, h2), od, 0, 0, 0);
;     od = __builtin_amdgcn_mfma_f32_32x32x16_bf16(pa3, PK(l3, h3), od, 0, 0, 0);
;     ...
; }
; template <int D> DI void pv_all(f32x16* o, int vb, bf16x8 pa0, bf16x8 pa1, bf16x8 pa2, bf16x8 pa3) {
;     pv_one<D, 0>(o[0], vb, pa0, pa1, pa2, pa3); pv_one<D, 1>(o[1], vb, pa0, pa1, pa2, pa3);
;     if constexpr (D == 128) { pv_one<D, 2>(o[2], vb, pa0, pa1, pa2, pa3); pv_one<D, 3>(o[3], vb, pa0, pa1, pa2, pa3); }
; template <int D, bool PIPE, class Seq, class MaskF, class KX>
; DI void run_tiles(Core<D>& c, char* kv, float* ws, const bf16_t* Kg0, const bf16_t* Vg0, int pitch, const Seq& seq, const MaskF& mk, const KX& kx, int tid_, int lane_) {
;     ...
;         for (;;) {
;             int t1 = 0; const bool e1 = seq.next(t0, t1);
;             if (e1) { stg_ld<D>(sk, Kg0 + (size_t)64 * t1 * pitch, pitch, tid); stg_ld<D>(sv, Vg0 + (size_t)64 * t1 * pitch, pitch, tid); }
;             f32x16 p0, p1; qkt<D>(p0, p1, kv + buf * KB, c.qr, r32, hi);
;             tile_finish<D>(c, p0, p1, t0, mk, ws, vb0 + buf * KB, r32, hi);
;             if (e1) { kx.apply(sk, t1, tid); stg_wrK<D>(sk, kv + (buf ^ 1) * KB, tid); stg_wrV<D>(sv, kv + 2 * KB + (buf ^ 1) * KB, tid); }
;             LBAR();
;             if (!e1) break;
;             t0 = t1; buf ^= 1;
;         }
.Lpv_fast_sel:
	s_waitcnt lgkmcnt(0)
	s_nop 0
	v_mfma_f32_32x32x16_bf16 v[50:65], v[66:69], v[84:87], v[50:65]
	ds_read_b64_tr_b16 v[84:85], v96 offset:0x200
	ds_read_b64_tr_b16 v[86:87], v96 offset:0xa00
	v_mfma_f32_32x32x16_bf16 v[50:65], v[70:73], v[88:91], v[50:65]
	ds_read_b64_tr_b16 v[88:89], v96 offset:0x1200
	ds_read_b64_tr_b16 v[90:91], v96 offset:0x1a00
	v_mfma_f32_32x32x16_bf16 v[50:65], v[74:77], v[92:95], v[50:65]
	ds_read_b64_tr_b16 v[92:93], v96 offset:0x2200
	ds_read_b64_tr_b16 v[94:95], v96 offset:0x2a00
	v_mfma_f32_32x32x16_bf16 v[50:65], v[78:81], v[186:189], v[50:65]
	ds_read_b64_tr_b16 v[186:187], v96 offset:0x3200
	ds_read_b64_tr_b16 v[188:189], v96 offset:0x3a00
	s_waitcnt lgkmcnt(0)
	s_cmp_eq_u64 s[52:53], 0
	s_cbranch_scc1 .Lew_sel_skip
	s_xor_b32 s99, s61, 0x4000
	v_add_u32_e32 v195, s99, v214
	v_add_u32_e32 v196, s99, v215
	s_waitcnt vmcnt(1)
	ds_write_b128 v195, v[106:109] offset:32768
	s_waitcnt vmcnt(0)
	ds_write_b128 v196, v[144:147] offset:32768
.Lew_sel_skip:
	v_mfma_f32_32x32x16_bf16 v[34:49], v[66:69], v[84:87], v[34:49]
	ds_read_b64_tr_b16 v[84:85], v96 offset:0x400
	ds_read_b64_tr_b16 v[86:87], v96 offset:0xc00
	v_mfma_f32_32x32x16_bf16 v[34:49], v[70:73], v[88:91], v[34:49]
	ds_read_b64_tr_b16 v[88:89], v96 offset:0x1400
	ds_read_b64_tr_b16 v[90:91], v96 offset:0x1c00
	v_mfma_f32_32x32x16_bf16 v[34:49], v[74:77], v[92:95], v[34:49]
	ds_read_b64_tr_b16 v[92:93], v96 offset:0x2400
	ds_read_b64_tr_b16 v[94:95], v96 offset:0x2c00
	v_mfma_f32_32x32x16_bf16 v[34:49], v[78:81], v[186:189], v[34:49]
	ds_read_b64_tr_b16 v[186:187], v96 offset:0x3400
	ds_read_b64_tr_b16 v[188:189], v96 offset:0x3c00
	s_waitcnt lgkmcnt(0)
	v_mfma_f32_32x32x16_bf16 v[18:33], v[66:69], v[84:87], v[18:33]
	ds_read_b64_tr_b16 v[84:85], v96 offset:0x600
	ds_read_b64_tr_b16 v[86:87], v96 offset:0xe00
	v_mfma_f32_32x32x16_bf16 v[18:33], v[70:73], v[88:91], v[18:33]
	ds_read_b64_tr_b16 v[88:89], v96 offset:0x1600
	ds_read_b64_tr_b16 v[90:91], v96 offset:0x1e00
	v_mfma_f32_32x32x16_bf16 v[18:33], v[74:77], v[92:95], v[18:33]
	ds_read_b64_tr_b16 v[92:93], v96 offset:0x2600
	ds_read_b64_tr_b16 v[94:95], v96 offset:0x2e00
	v_mfma_f32_32x32x16_bf16 v[18:33], v[78:81], v[186:189], v[18:33]
	ds_read_b64_tr_b16 v[186:187], v96 offset:0x3600
	ds_read_b64_tr_b16 v[188:189], v96 offset:0x3e00
	s_waitcnt lgkmcnt(0)
	v_mfma_f32_32x32x16_bf16 v[2:17], v[66:69], v[84:87], v[2:17]
	v_cndmask_b32_e64 v67, 0, 1, s[52:53]
	s_andn2_b64 vcc, exec, s[52:53]
	v_mfma_f32_32x32x16_bf16 v[2:17], v[70:73], v[88:91], v[2:17]
	v_mfma_f32_32x32x16_bf16 v[2:17], v[74:77], v[92:95], v[2:17]
	v_mfma_f32_32x32x16_bf16 v[2:17], v[78:81], v[186:189], v[2:17]
	s_cbranch_vccnz .LBB0_873
	s_mov_b32 s59, s60

; #define SBAR() __builtin_amdgcn_sched_barrier(0)
; #pragma unroll
;     for (int r = 0; r < 16; ++r) { p0[r] = 0.f; p1[r] = 0.f; }
;     int rowb = r32 * (2 * D), swz = (r32 & 7) << 4; asm volatile("" : "+v"(rowb), "+v"(swz));
; #pragma unroll
;     for (int g4 = 0; g4 < D / (16 * NBT); ++g4) {
;         bf16x8 kf[2 * NBT];
; #pragma unroll
;         for (int i = 0; i < NBT; ++i) { const int cb = ((g4 * NBT + i) * 16 + hi * 8) * 2;
;             const char* kp = Ks + rowb + (cb ^ swz);
;             kf[2 * i] = *reinterpret_cast<const bf16x8*>(kp);
;             kf[2 * i + 1] = *reinterpret_cast<const bf16x8*>(kp + 64 * D); }
;         SBAR();
; #pragma unroll
;         for (int i = 0; i < NBT; ++i) {
;             p0 = __builtin_amdgcn_mfma_f32_32x32x16_bf16(kf[2 * i], qr[g4 * NBT + i], p0, 0, 0, 0);
;             p1 = __builtin_amdgcn_mfma_f32_32x32x16_bf16(kf[2 * i + 1], qr[g4 * NBT + i], p1, 0, 0, 0); }
;         SBAR();
;     }
; }
; template <int D, bool PIPE, class Seq, class MaskF, class KX>
; DI void run_tiles(Core<D>& c, char* kv, float* ws, const bf16_t* Kg0, const bf16_t* Vg0, int pitch, const Seq& seq, const MaskF& mk, const KX& kx, int tid_, int lane_) {
;     ...
;         for (;;) {
;             int t1 = 0; const bool e1 = seq.next(t0, t1);
;             if (e1) { stg_ld<D>(sk, Kg0 + (size_t)64 * t1 * pitch, pitch, tid); stg_ld<D>(sv, Vg0 + (size_t)64 * t1 * pitch, pitch, tid); }
;             f32x16 p0, p1; qkt<D>(p0, p1, kv + buf * KB, c.qr, r32, hi);
;             tile_finish<D>(c, p0, p1, t0, mk, ws, vb0 + buf * KB, r32, hi);
;             if (e1) { kx.apply(sk, t1, tid); stg_wrK<D>(sk, kv + (buf ^ 1) * KB, tid); stg_wrV<D>(sv, kv + 2 * KB + (buf ^ 1) * KB, tid); }
.LBB0_883:
	s_lshl_b32 s93, s10, 14
	s_add_i32 s14, s93, 0
	v_mov_b32_e32 v66, v175
	v_mov_b32_e32 v217, v176
	v_add_u32_e32 v74, 32, v177
	v_add_u32_e32 v234, s14, v66
	v_xad_u32 v70, v217, v177, v234
	v_xad_u32 v74, v217, v74, v234
	ds_read_b128 v[66:69], v70
	ds_read_b128 v[70:73], v70 offset:8192
	ds_read_b128 v[186:189], v74
	ds_read_b128 v[194:197], v74 offset:8192
	v_add_u32_e32 v74, 64, v177
	v_xad_u32 v74, v217, v74, v234
	ds_read_b128 v[218:221], v74
	ds_read_b128 v[222:225], v74 offset:8192
	v_xad_u32 v74, v217, v206, v234
	ds_read_b128 v[226:229], v74
	ds_read_b128 v[230:233], v74 offset:8192
	s_waitcnt lgkmcnt(7)
	v_mfma_f32_32x32x16_bf16 v[82:97], v[66:69], v[112:115], 0
	s_waitcnt lgkmcnt(6)
	v_mfma_f32_32x32x16_bf16 v[66:81], v[70:73], v[112:115], 0
	s_waitcnt lgkmcnt(5)
	v_mfma_f32_32x32x16_bf16 v[82:97], v[186:189], v[116:119], v[82:97]
	v_xad_u32 v238, v217, v207, v234
	v_xad_u32 v239, v217, v208, v234
	v_xad_u32 v253, v217, v209, v234
	v_xad_u32 v217, v217, v210, v234
	ds_read_b128 v[186:189], v238
	s_waitcnt lgkmcnt(5)
	v_mfma_f32_32x32x16_bf16 v[66:81], v[194:197], v[116:119], v[66:81]
	ds_read_b128 v[194:197], v238 offset:8192
	s_waitcnt lgkmcnt(5)
	v_mfma_f32_32x32x16_bf16 v[82:97], v[218:221], v[120:123], v[82:97]
	ds_read_b128 v[218:221], v239
	s_waitcnt lgkmcnt(5)
	v_mfma_f32_32x32x16_bf16 v[66:81], v[222:225], v[120:123], v[66:81]
	ds_read_b128 v[222:225], v239 offset:8192
	s_waitcnt lgkmcnt(5)
	v_mfma_f32_32x32x16_bf16 v[82:97], v[226:229], v[124:127], v[82:97]
	ds_read_b128 v[226:229], v253
	s_waitcnt lgkmcnt(5)
	v_mfma_f32_32x32x16_bf16 v[66:81], v[230:233], v[124:127], v[66:81]
	ds_read_b128 v[230:233], v253 offset:8192
	ds_read_b128 v[234:237], v217
	ds_read_b128 v[248:251], v217 offset:8192
	s_waitcnt lgkmcnt(7)
	v_mfma_f32_32x32x16_bf16 v[82:97], v[186:189], v[128:131], v[82:97]
	s_waitcnt lgkmcnt(6)
	v_mfma_f32_32x32x16_bf16 v[66:81], v[194:197], v[128:131], v[66:81]
	s_waitcnt lgkmcnt(5)
	v_mfma_f32_32x32x16_bf16 v[82:97], v[218:221], v[132:135], v[82:97]
	s_waitcnt lgkmcnt(4)
	v_mfma_f32_32x32x16_bf16 v[66:81], v[222:225], v[132:135], v[66:81]
	s_waitcnt lgkmcnt(3)
	v_mfma_f32_32x32x16_bf16 v[82:97], v[226:229], v[136:139], v[82:97]
	s_waitcnt lgkmcnt(2)
	v_mfma_f32_32x32x16_bf16 v[66:81], v[230:233], v[136:139], v[66:81]
	s_waitcnt lgkmcnt(1)
	v_mfma_f32_32x32x16_bf16 v[82:97], v[234:237], v[140:143], v[82:97]
	s_waitcnt lgkmcnt(0)
	v_mfma_f32_32x32x16_bf16 v[66:81], v[248:251], v[140:143], v[66:81]
	s_cmp_eq_u64 s[2:3], 0
	s_cbranch_scc1 .Lew_win_kskip
	s_xor_b32 s99, s93, 0x4000
	v_add_u32_e32 v194, s99, v205
	s_waitcnt vmcnt(3)
	ds_write_b128 v194, v[98:101]
	s_waitcnt vmcnt(2)
	ds_write_b128 v194, v[102:105] offset:8192
; DI int crow(int r, int hi) { return (r & 3) + 8 * (r >> 2) + 4 * hi; }
; template <int D, class MaskF>
; DI void tile_finish(Core<D>& c, f32x16& p0, f32x16& p1, int j, const MaskF& mk, float* ws, int vb, int r32, int hi) {
;     if (mk.partial(j)) { const int kb = 64 * j;
; #pragma unroll
;         for (int r = 0; r < 16; ++r) { const int k0 = kb + crow(r, hi); if (!mk.ok(j, k0)) p0[r] = NEGS; if (!mk.ok(j, k0 + 32)) p1[r] = NEGS; } }
.Lew_win_kskip:
	s_lshl_b32 s14, s92, 6
	s_or_b32 s15, s14, 63
	s_cmp_gt_i32 s15, s86
	s_cselect_b64 s[16:17], -1, 0
	s_cmp_le_i32 s14, s90
	s_cselect_b64 s[18:19], -1, 0
	s_or_b64 s[16:17], s[16:17], s[18:19]
	s_andn2_b64 vcc, exec, s[16:17]
	s_cbranch_vccnz .LBB0_887
	v_add_u32_e32 v186, s14, v203
	v_add_u32_e32 v187, 32, v186
	v_cmp_le_i32_e64 s[16:17], v187, v169
	v_cmp_gt_i32_e64 s[18:19], v187, v174
	v_add_u32_e32 v187, 33, v186
	v_cmp_le_i32_e64 s[20:21], v187, v169
	v_cmp_gt_i32_e64 s[22:23], v187, v174
	s_and_b64 s[20:21], s[20:21], s[22:23]
	v_or_b32_e32 v187, 2, v186
	v_cndmask_b32_e64 v67, v247, v67, s[20:21]
	v_cmp_le_i32_e64 s[20:21], v187, v169
	v_cmp_gt_i32_e64 s[22:23], v187, v174
	v_add_u32_e32 v187, 34, v186
	v_cmp_le_i32_e64 s[24:25], v187, v169
	v_cmp_gt_i32_e64 s[26:27], v187, v174
	s_and_b64 s[24:25], s[24:25], s[26:27]
	v_or_b32_e32 v187, 3, v186
	v_cndmask_b32_e64 v68, v247, v68, s[24:25]
	v_cmp_le_i32_e64 s[24:25], v187, v169
	v_cmp_gt_i32_e64 s[26:27], v187, v174
	v_add_u32_e32 v187, 35, v186
	v_cmp_le_i32_e64 s[28:29], v187, v169
	v_cmp_gt_i32_e64 s[30:31], v187, v174
	s_and_b64 s[28:29], s[28:29], s[30:31]
	v_add_u32_e32 v187, 8, v186
	v_cndmask_b32_e64 v69, v247, v69, s[28:29]
	v_cmp_le_i32_e64 s[28:29], v187, v169
	v_cmp_gt_i32_e64 s[30:31], v187, v174
	v_add_u32_e32 v187, 40, v186
	v_cmp_le_i32_e64 s[34:35], v187, v169
	v_cmp_gt_i32_e64 s[36:37], v187, v174
	s_and_b64 s[34:35], s[34:35], s[36:37]
	v_add_u32_e32 v187, 9, v186
	v_cndmask_b32_e64 v70, v247, v70, s[34:35]
	v_cmp_le_i32_e64 s[34:35], v187, v169
	v_cmp_gt_i32_e64 s[36:37], v187, v174
	v_add_u32_e32 v187, 41, v186
	v_cmp_le_i32_e64 s[38:39], v187, v169
	v_cmp_gt_i32_e64 s[40:41], v187, v174
	s_and_b64 s[38:39], s[38:39], s[40:41]
	v_add_u32_e32 v187, 10, v186
	v_cndmask_b32_e64 v71, v247, v71, s[38:39]
	v_cmp_le_i32_e64 s[38:39], v187, v169
	v_cmp_gt_i32_e64 s[40:41], v187, v174
	v_add_u32_e32 v187, 42, v186
	v_cmp_le_i32_e64 s[42:43], v187, v169
	v_cmp_gt_i32_e64 s[44:45], v187, v174
	s_and_b64 s[42:43], s[42:43], s[44:45]
	v_add_u32_e32 v187, 11, v186
	v_cndmask_b32_e64 v72, v247, v72, s[42:43]
	v_cmp_le_i32_e64 s[42:43], v187, v169
	v_cmp_gt_i32_e64 s[44:45], v187, v174
	v_add_u32_e32 v187, 43, v186
	v_cmp_le_i32_e64 s[46:47], v187, v169
	v_cmp_gt_i32_e64 s[48:49], v187, v174
	s_and_b64 s[46:47], s[46:47], s[48:49]
	v_add_u32_e32 v187, 16, v186
	v_cndmask_b32_e64 v73, v247, v73, s[46:47]
	v_cmp_le_i32_e64 s[46:47], v187, v169
	v_cmp_gt_i32_e64 s[48:49], v187, v174
	v_add_u32_e32 v187, 48, v186
	v_cmp_le_i32_e64 s[50:51], v187, v169
	v_cmp_gt_i32_e64 s[52:53], v187, v174
	s_and_b64 s[50:51], s[50:51], s[52:53]
	v_add_u32_e32 v187, 17, v186
	v_cndmask_b32_e64 v74, v247, v74, s[50:51]
	v_cmp_le_i32_e64 s[50:51], v187, v169
	v_cmp_gt_i32_e64 s[52:53], v187, v174
	v_add_u32_e32 v187, 49, v186
	v_cmp_le_i32_e64 s[54:55], v187, v169
	v_cmp_gt_i32_e64 s[56:57], v187, v174
	s_and_b64 s[54:55], s[54:55], s[56:57]
	v_add_u32_e32 v187, 18, v186
	v_cndmask_b32_e64 v75, v247, v75, s[54:55]
	v_cmp_le_i32_e64 s[54:55], v187, v169
	v_cmp_gt_i32_e64 s[56:57], v187, v174
	v_add_u32_e32 v187, 50, v186
	v_cmp_le_i32_e64 s[58:59], v187, v169
	v_cmp_gt_i32_e64 s[60:61], v187, v174
	s_and_b64 s[58:59], s[58:59], s[60:61]
	v_add_u32_e32 v187, 19, v186
	v_cndmask_b32_e64 v76, v247, v76, s[58:59]
	v_cmp_le_i32_e64 s[58:59], v187, v169
	v_cmp_gt_i32_e64 s[60:61], v187, v174
	v_add_u32_e32 v187, 51, v186
	v_cmp_le_i32_e64 s[62:63], v187, v169
	v_cmp_gt_i32_e64 s[64:65], v187, v174
	s_and_b64 s[62:63], s[62:63], s[64:65]
	v_add_u32_e32 v187, 24, v186
	v_cndmask_b32_e64 v77, v247, v77, s[62:63]
	v_cmp_le_i32_e64 s[62:63], v187, v169
	v_cmp_gt_i32_e64 s[64:65], v187, v174
	v_add_u32_e32 v187, 56, v186
	v_cmp_le_i32_e64 s[66:67], v187, v169
	v_cmp_gt_i32_e64 s[68:69], v187, v174
	s_and_b64 s[66:67], s[66:67], s[68:69]
	v_add_u32_e32 v187, 25, v186
	v_cndmask_b32_e64 v78, v247, v78, s[66:67]
	v_cmp_le_i32_e64 s[66:67], v187, v169
	v_cmp_gt_i32_e64 s[68:69], v187, v174
	v_add_u32_e32 v187, 57, v186
	v_cmp_le_i32_e64 s[70:71], v187, v169
	v_cmp_gt_i32_e64 s[72:73], v187, v174
	s_and_b64 s[70:71], s[70:71], s[72:73]
	v_add_u32_e32 v187, 26, v186
	s_and_b64 s[16:17], s[16:17], s[18:19]
	v_cndmask_b32_e64 v79, v247, v79, s[70:71]
	v_cmp_le_i32_e64 s[70:71], v187, v169
	v_cmp_gt_i32_e64 s[72:73], v187, v174
	v_add_u32_e32 v187, 58, v186
	v_cmp_le_i32_e32 vcc, v186, v169
	v_cmp_gt_i32_e64 s[14:15], v186, v174
	v_cndmask_b32_e64 v66, v247, v66, s[16:17]
	v_cmp_lt_i32_e64 s[16:17], v186, v169
	v_cmp_ge_i32_e64 s[18:19], v186, v174
	v_cmp_le_i32_e64 s[74:75], v187, v169
	v_cmp_gt_i32_e64 s[76:77], v187, v174
	v_add_u32_e32 v187, 27, v186
	v_add_u32_e32 v186, 59, v186
	s_and_b64 s[74:75], s[74:75], s[76:77]
	v_cmp_gt_i32_e64 s[78:79], v186, v169
	v_cmp_le_i32_e64 s[80:81], v186, v174
	v_cndmask_b32_e64 v80, v247, v80, s[74:75]
	v_cmp_le_i32_e64 s[74:75], v187, v169
	v_cmp_gt_i32_e64 s[76:77], v187, v174
	s_or_b64 s[80:81], s[78:79], s[80:81]
	s_and_saveexec_b64 s[78:79], s[80:81]
	v_mov_b32_e32 v81, s95
	s_or_b64 exec, exec, s[78:79]
	s_and_b64 vcc, vcc, s[14:15]
	v_cndmask_b32_e32 v82, v247, v82, vcc
	s_and_b64 vcc, s[16:17], s[18:19]
	v_cndmask_b32_e32 v83, v247, v83, vcc
	s_and_b64 vcc, s[20:21], s[22:23]
	v_cndmask_b32_e32 v84, v247, v84, vcc
	s_and_b64 vcc, s[24:25], s[26:27]
	v_cndmask_b32_e32 v85, v247, v85, vcc
	s_and_b64 vcc, s[28:29], s[30:31]
	v_cndmask_b32_e32 v86, v247, v86, vcc
	s_and_b64 vcc, s[34:35], s[36:37]
	v_cndmask_b32_e32 v87, v247, v87, vcc
	s_and_b64 vcc, s[38:39], s[40:41]
	v_cndmask_b32_e32 v88, v247, v88, vcc
	s_and_b64 vcc, s[42:43], s[44:45]
	v_cndmask_b32_e32 v89, v247, v89, vcc
	s_and_b64 vcc, s[46:47], s[48:49]
	v_cndmask_b32_e32 v90, v247, v90, vcc
	s_and_b64 vcc, s[50:51], s[52:53]
	v_cndmask_b32_e32 v91, v247, v91, vcc
	s_and_b64 vcc, s[54:55], s[56:57]
	v_cndmask_b32_e32 v92, v247, v92, vcc
	s_and_b64 vcc, s[58:59], s[60:61]
	v_cndmask_b32_e32 v93, v247, v93, vcc
	s_and_b64 vcc, s[62:63], s[64:65]
	v_cndmask_b32_e32 v94, v247, v94, vcc
	s_and_b64 vcc, s[66:67], s[68:69]
	v_cndmask_b32_e32 v95, v247, v95, vcc
	s_and_b64 vcc, s[70:71], s[72:73]
	v_cndmask_b32_e32 v96, v247, v96, vcc
	s_and_b64 vcc, s[74:75], s[76:77]
	v_cndmask_b32_e32 v97, v247, v97, vcc

; #define SBAR() __builtin_amdgcn_sched_barrier(0)
; template <int OFF> DI s16x4 tr_read(int vb) { s16x4 r; asm volatile("ds_read_b64_tr_b16 %0, %1 offset:%2" : "=&v"(r) : "v"(vb), "i"(OFF) : "memory"); return r; }
; #define LBAR() asm volatile("s_waitcnt lgkmcnt(0)\n\ts_barrier" ::: "memory")
; template <int D, int D0> DI void pv_one(f32x16& od, int vb, bf16x8 pa0, bf16x8 pa1, bf16x8 pa2, bf16x8 pa3) {
;     const s16x4 l0 = tr_read<v_rd_off<D>(D0, 0, 0)>(vb), h0 = tr_read<v_rd_off<D>(D0, 0, 1)>(vb), l1 = tr_read<v_rd_off<D>(D0, 1, 0)>(vb), h1 = tr_read<v_rd_off<D>(D0, 1, 1)>(vb);
;     const s16x4 l2 = tr_read<v_rd_off<D>(D0, 2, 0)>(vb), h2 = tr_read<v_rd_off<D>(D0, 2, 1)>(vb), l3 = tr_read<v_rd_off<D>(D0, 3, 0)>(vb), h3 = tr_read<v_rd_off<D>(D0, 3, 1)>(vb);
;     asm volatile("s_waitcnt lgkmcnt(0)" ::: "memory"); SBAR();
;     ...
;     od = __builtin_amdgcn_mfma_f32_32x32x16_bf16(pa0, PK(l0, h0), od, 0, 0, 0);
;     od = __builtin_amdgcn_mfma_f32_32x32x16_bf16(pa1, PK(l1, h1), od, 0, 0, 0);
;     od = __builtin_amdgcn_mfma_f32_32x32x16_bf16(pa2, PK(l2, h2), od, 0, 0, 0);
;     od = __builtin_amdgcn_mfma_f32_32x32x16_bf16(pa3, PK(l3, h3), od, 0, 0, 0);
;     ...
; }
; template <int D> DI void pv_all(f32x16* o, int vb, bf16x8 pa0, bf16x8 pa1, bf16x8 pa2, bf16x8 pa3) {
;     pv_one<D, 0>(o[0], vb, pa0, pa1, pa2, pa3); pv_one<D, 1>(o[1], vb, pa0, pa1, pa2, pa3);
;     if constexpr (D == 128) { pv_one<D, 2>(o[2], vb, pa0, pa1, pa2, pa3); pv_one<D, 3>(o[3], vb, pa0, pa1, pa2, pa3); }
; template <int D, bool PIPE, class Seq, class MaskF, class KX>
; DI void run_tiles(Core<D>& c, char* kv, float* ws, const bf16_t* Kg0, const bf16_t* Vg0, int pitch, const Seq& seq, const MaskF& mk, const KX& kx, int tid_, int lane_) {
;     ...
;         for (;;) {
;             int t1 = 0; const bool e1 = seq.next(t0, t1);
;             if (e1) { stg_ld<D>(sk, Kg0 + (size_t)64 * t1 * pitch, pitch, tid); stg_ld<D>(sv, Vg0 + (size_t)64 * t1 * pitch, pitch, tid); }
;             f32x16 p0, p1; qkt<D>(p0, p1, kv + buf * KB, c.qr, r32, hi);
;             tile_finish<D>(c, p0, p1, t0, mk, ws, vb0 + buf * KB, r32, hi);
;             if (e1) { kx.apply(sk, t1, tid); stg_wrK<D>(sk, kv + (buf ^ 1) * KB, tid); stg_wrV<D>(sv, kv + 2 * KB + (buf ^ 1) * KB, tid); }
;             LBAR();
;             if (!e1) break;
;             t0 = t1; buf ^= 1;
;         }
.Lpv_fast_win:
	s_waitcnt lgkmcnt(0)
	s_nop 0
	v_mfma_f32_32x32x16_bf16 v[50:65], v[66:69], v[84:87], v[50:65]
	ds_read_b64_tr_b16 v[84:85], v96 offset:0x200
	ds_read_b64_tr_b16 v[86:87], v96 offset:0xa00
	v_mfma_f32_32x32x16_bf16 v[50:65], v[70:73], v[88:91], v[50:65]
	ds_read_b64_tr_b16 v[88:89], v96 offset:0x1200
	ds_read_b64_tr_b16 v[90:91], v96 offset:0x1a00
	v_mfma_f32_32x32x16_bf16 v[50:65], v[74:77], v[92:95], v[50:65]
	ds_read_b64_tr_b16 v[92:93], v96 offset:0x2200
	ds_read_b64_tr_b16 v[94:95], v96 offset:0x2a00
	v_mfma_f32_32x32x16_bf16 v[50:65], v[78:81], v[186:189], v[50:65]
	ds_read_b64_tr_b16 v[186:187], v96 offset:0x3200
	ds_read_b64_tr_b16 v[188:189], v96 offset:0x3a00
	s_waitcnt lgkmcnt(0)
	s_cmp_eq_u64 s[2:3], 0
	s_cbranch_scc1 .Lew_win_skip
	s_xor_b32 s99, s93, 0x4000
	v_add_u32_e32 v195, s99, v212
	v_add_u32_e32 v196, s99, v213
	s_waitcnt vmcnt(1)
	ds_write_b128 v195, v[106:109] offset:32768
	s_waitcnt vmcnt(0)
	ds_write_b128 v196, v[144:147] offset:32768
.Lew_win_skip:
	v_mfma_f32_32x32x16_bf16 v[34:49], v[66:69], v[84:87], v[34:49]
	ds_read_b64_tr_b16 v[84:85], v96 offset:0x400
	ds_read_b64_tr_b16 v[86:87], v96 offset:0xc00
	v_mfma_f32_32x32x16_bf16 v[34:49], v[70:73], v[88:91], v[34:49]
	ds_read_b64_tr_b16 v[88:89], v96 offset:0x1400
	ds_read_b64_tr_b16 v[90:91], v96 offset:0x1c00
	v_mfma_f32_32x32x16_bf16 v[34:49], v[74:77], v[92:95], v[34:49]
	ds_read_b64_tr_b16 v[92:93], v96 offset:0x2400
	ds_read_b64_tr_b16 v[94:95], v96 offset:0x2c00
	v_mfma_f32_32x32x16_bf16 v[34:49], v[78:81], v[186:189], v[34:49]
	ds_read_b64_tr_b16 v[186:187], v96 offset:0x3400
	ds_read_b64_tr_b16 v[188:189], v96 offset:0x3c00
	s_waitcnt lgkmcnt(0)
	v_mfma_f32_32x32x16_bf16 v[18:33], v[66:69], v[84:87], v[18:33]
	ds_read_b64_tr_b16 v[84:85], v96 offset:0x600
	ds_read_b64_tr_b16 v[86:87], v96 offset:0xe00
	v_mfma_f32_32x32x16_bf16 v[18:33], v[70:73], v[88:91], v[18:33]
	ds_read_b64_tr_b16 v[88:89], v96 offset:0x1600
	ds_read_b64_tr_b16 v[90:91], v96 offset:0x1e00
	v_mfma_f32_32x32x16_bf16 v[18:33], v[74:77], v[92:95], v[18:33]
	ds_read_b64_tr_b16 v[92:93], v96 offset:0x2600
	ds_read_b64_tr_b16 v[94:95], v96 offset:0x2e00
	v_mfma_f32_32x32x16_bf16 v[18:33], v[78:81], v[186:189], v[18:33]
	ds_read_b64_tr_b16 v[186:187], v96 offset:0x3600
	ds_read_b64_tr_b16 v[188:189], v96 offset:0x3e00
	s_waitcnt lgkmcnt(0)
	v_mfma_f32_32x32x16_bf16 v[2:17], v[66:69], v[84:87], v[2:17]
	v_cndmask_b32_e64 v66, 0, 1, s[2:3]
	s_andn2_b64 vcc, exec, s[2:3]
	v_mfma_f32_32x32x16_bf16 v[2:17], v[70:73], v[88:91], v[2:17]
	v_mfma_f32_32x32x16_bf16 v[2:17], v[74:77], v[92:95], v[2:17]
	v_mfma_f32_32x32x16_bf16 v[2:17], v[78:81], v[186:189], v[2:17]
	s_cbranch_vccnz .LBB0_894
	s_mov_b32 s92, s88
